# P3 item prologue: the step loop's first two u fragments are loaded at the top of the prologue instead of at its end (no exposed round trip before the loop)
# baseline (speedup 1.0000x reference)
; template <bool FINAL>
; __device__ __forceinline__ void ssm_item(const Args& a, LAS unsigned char* lds, int item, int wave, int lane) {
;     ...
;     bf16x8 bbf[4];
; #pragma unroll
;     for (int k = 0; k < 4; ++k) bbf[k] = *(const bf16x8*)((const bf16*)(ws + WS_BB) + ((size_t)g * 128 + k * 32 + j) * 16 + 8 * hi);
;     const f32x2 a0 = ((const f32x2*)(ws + WS_ATAB))[g * 64 + j], a1 = ((const f32x2*)(ws + WS_ATAB))[g * 64 + 32 + j];
;     const f32x2 a0x = (f32x2){a0.x, a0.x}, a0y = (f32x2){a0.y, a0.y}, na0y = (f32x2){-a0.y, -a0.y}, a1x = (f32x2){a1.x, a1.x}, a1y = (f32x2){a1.y, a1.y}, na1y = (f32x2){-a1.y, -a1.y};
;     f32x2 s0r = (f32x2){0.f, 0.f}, s0i = s0r, s1r = s0r, s1i = s0r;
;     bf16x8 cmf[4]; f32x4 dsk;
;     if (FINAL) {
; #pragma unroll
;         for (int k = 0; k < 4; ++k) cmf[k] = *(const bf16x8*)((const bf16*)(ws + WS_CM) + ((size_t)g * 16 + (lane & 15)) * 128 + 32 * k + 8 * (lane >> 4));
;         dsk = *(const f32x4*)(a.in[14] + g * 16 + 4 * (lane >> 4));
;         const f32x2 t0 = ((const f32x2*)(ws + WS_ATAB2))[g * 64 + j], t1 = ((const f32x2*)(ws + WS_ATAB2))[g * 64 + 32 + j];
;         const f32x2 m0 = ((const f32x2*)(ws + WS_SMETA))[g * 64 + j], m1 = ((const f32x2*)(ws + WS_SMETA))[g * 64 + 32 + j];
;         float c0r = m0.x, c0i = m0.y, c1r = m1.x, c1i = m1.y;
;         const f32x2* Eb = (const f32x2*)E + ((size_t)((b0 + hi) * 64 + g) * NCHUNK) * 64;
; #pragma unroll
;         for (int half = 0; half < 2; ++half) {
;             if (half * 16 < c0) {
;                 f32x2 e0[16], e1[16];
; #pragma unroll
;                 for (int c = 0; c < 16; ++c) { const int cc = half * 16 + c < NCHUNK - 1 ? half * 16 + c : NCHUNK - 2; e0[c] = Eb[cc * 64 + j]; e1[c] = Eb[cc * 64 + 32 + j]; }
; #pragma unroll
;                 for (int c = 0; c < 16; ++c) if (half * 16 + c < c0) {
;                     const float n0r = fmaf(t0.x, c0r, fmaf(-t0.y, c0i, e0[c].x)), n0i = fmaf(t0.x, c0i, fmaf(t0.y, c0r, e0[c].y));
;                     const float n1r = fmaf(t1.x, c1r, fmaf(-t1.y, c1i, e1[c].x)), n1i = fmaf(t1.x, c1i, fmaf(t1.y, c1r, e1[c].y));
;                     c0r = n0r; c0i = n0i; c1r = n1r; c1i = n1i; }
;             }
;         }
;         const f32x2 ec0 = Eb[c0 * 64 + j], ec1 = Eb[c0 * 64 + 32 + j];
;         s0r = (f32x2){c0r, fmaf(t0.x, c0r, fmaf(-t0.y, c0i, ec0.x))}; s0i = (f32x2){c0i, fmaf(t0.x, c0i, fmaf(t0.y, c0r, ec0.y))};
.LBB0_328:
	s_lshl_b32 s10, s20, 3
	s_and_b32 s10, s10, 56
	s_add_i32 s22, s10, s33
	s_mov_b32 s23, s11
	s_lshl_b64 s[12:13], s[22:23], 12
	s_lshl_b32 s10, s22, 6
	s_lshr_b32 s66, s20, 6
	s_and_b32 s66, s66, 2
	s_lshr_b32 s67, s20, 2
	s_and_b32 s67, s67, 30
	s_lshl_b32 s68, s22, 5
	v_or_b32_e32 v220, s66, v163
	v_or_b32_e32 v221, s67, v165
	v_lshlrev_b32_e32 v220, 13, v220
	v_lshlrev_b32_e32 v221, 8, v221
	v_or3_b32 v220, v220, v221, v167
	v_lshlrev_b32_e32 v220, 11, v220
	v_add3_u32 v220, v220, s68, v188
	v_add_u32_e32 v221, 0x4000, v220
	global_load_dwordx4 v[252:255], v220, s[52:53]
	global_load_dwordx4 v[248:251], v221, s[52:53]
	v_lshl_add_u64 v[0:1], v[108:109], 0, s[12:13]
	v_or_b32_e32 v106, s10, v130
	global_load_dwordx4 v[88:91], v[0:1], off
	global_load_dwordx4 v[92:95], v[0:1], off offset:1024
	global_load_dwordx4 v[96:99], v[0:1], off offset:2048
	global_load_dwordx4 v[84:87], v[0:1], off offset:3072
	v_lshlrev_b64 v[0:1], 3, v[106:107]
	v_or_b32_e32 v106, s10, v104
	v_lshl_add_u64 v[2:3], s[0:1], 0, v[0:1]
	v_lshlrev_b64 v[4:5], 3, v[106:107]
	v_lshl_add_u64 v[6:7], s[0:1], 0, v[4:5]
	global_load_dwordx2 v[194:195], v[2:3], off
	global_load_dwordx2 v[192:193], v[6:7], off
	v_lshl_add_u64 v[2:3], v[110:111], 0, s[12:13]
	global_load_dwordx4 v[80:83], v[2:3], off
	global_load_dwordx4 v[76:79], v[2:3], off offset:64
	global_load_dwordx4 v[72:75], v[2:3], off offset:128
	global_load_dwordx4 v[68:71], v[2:3], off offset:192
	s_lshl_b32 s10, s22, 4
	v_lshl_add_u64 v[2:3], s[10:11], 2, v[112:113]
	global_load_dwordx4 v[64:67], v[2:3], off
	v_lshl_add_u64 v[2:3], s[6:7], 0, v[0:1]
	v_lshl_add_u64 v[6:7], s[6:7], 0, v[4:5]
	v_lshl_add_u64 v[8:9], s[8:9], 0, v[0:1]
	v_lshl_add_u64 v[4:5], s[8:9], 0, v[4:5]
	global_load_dwordx2 v[2:3], v[2:3], off
	s_nop 0
	global_load_dwordx2 v[0:1], v[6:7], off
	global_load_dwordx2 v[10:11], v[8:9], off
	global_load_dwordx2 v[12:13], v[4:5], off
	s_lshr_b32 s12, s20, 6
	s_and_b32 s12, s12, 2
	v_or_b32_e32 v4, s12, v105
	s_lshr_b32 s13, s20, 2
	v_lshl_add_u32 v106, v4, 6, s22
	s_and_b32 s13, s13, 30
	v_lshlrev_b64 v[4:5], 14, v[106:107]
	s_cmp_eq_u32 s13, 0
	v_lshl_add_u64 v[4:5], s[4:5], 0, v[4:5]
	v_lshlrev_b32_e32 v106, 3, v130
	s_waitcnt vmcnt(3)
	v_xor_b32_e32 v8, 0x80000000, v3
	s_waitcnt vmcnt(2)
	v_xor_b32_e32 v6, 0x80000000, v1
	s_cbranch_scc1 .LBB0_333
	v_mov_b32_e32 v121, v107
	v_mov_b32_e32 v123, v107
	v_lshl_add_u64 v[62:63], v[4:5], 0, v[106:107]
	v_mov_b32_e32 v119, v107
	v_lshl_add_u64 v[16:17], v[4:5], 0, v[120:121]
	v_lshl_add_u64 v[18:19], v[4:5], 0, v[122:123]
	v_mov_b32_e32 v125, v107
	v_mov_b32_e32 v127, v107
	v_lshl_add_u64 v[14:15], v[4:5], 0, v[118:119]
	v_lshl_add_u64 v[20:21], v[4:5], 0, v[124:125]
	v_lshl_add_u64 v[22:23], v[4:5], 0, v[126:127]
	global_load_dwordx2 v[100:101], v[16:17], off
	global_load_dwordx2 v[58:59], v[18:19], off
	global_load_dwordx2 v[52:53], v[20:21], off
	global_load_dwordx2 v[46:47], v[22:23], off
	global_load_dwordx2 v[200:201], v[14:15], off
	global_load_dwordx2 v[56:57], v[62:63], off offset:2560
	global_load_dwordx2 v[48:49], v[62:63], off offset:3072
	global_load_dwordx2 v[40:41], v[62:63], off offset:3584
	v_mov_b32_e32 v129, v107
	v_add_co_u32_e32 v18, vcc, s15, v62
	v_lshl_add_u64 v[14:15], v[4:5], 0, v[128:129]
	s_nop 0
	v_addc_co_u32_e32 v19, vcc, 0, v63, vcc
	global_load_dwordx2 v[50:51], v[14:15], off
	global_load_dwordx2 v[42:43], v[18:19], off
	global_load_dwordx2 v[36:37], v[18:19], off offset:512
	global_load_dwordx2 v[32:33], v[18:19], off offset:1024
	global_load_dwordx2 v[34:35], v[18:19], off offset:1536
	global_load_dwordx2 v[28:29], v[18:19], off offset:2048
	global_load_dwordx2 v[20:21], v[18:19], off offset:2560
	global_load_dwordx2 v[14:15], v[18:19], off offset:3072
	v_mov_b32_e32 v137, v107
	v_mov_b32_e32 v139, v107
	v_mov_b32_e32 v141, v107
	v_mov_b32_e32 v143, v107
	v_mov_b32_e32 v145, v107
	v_mov_b32_e32 v147, v107
	v_lshlrev_b32_e32 v38, 3, v104
	v_mov_b32_e32 v39, v107
	v_mov_b32_e32 v133, v107
	v_mov_b32_e32 v135, v107
	v_lshl_add_u64 v[54:55], v[4:5], 0, v[136:137]
	v_lshl_add_u64 v[24:25], v[4:5], 0, v[138:139]
	v_lshl_add_u64 v[30:31], v[4:5], 0, v[140:141]
	v_lshl_add_u64 v[60:61], v[4:5], 0, v[142:143]
	v_lshl_add_u64 v[102:103], v[4:5], 0, v[144:145]
	v_lshl_add_u64 v[16:17], v[4:5], 0, v[146:147]
	v_lshl_add_u64 v[38:39], v[4:5], 0, v[38:39]
	v_lshl_add_u64 v[22:23], v[4:5], 0, v[132:133]
	v_lshl_add_u64 v[26:27], v[4:5], 0, v[134:135]
	global_load_dwordx2 v[202:203], v[62:63], off offset:512
	global_load_dwordx2 v[198:199], v[62:63], off offset:1536
	global_load_dwordx2 v[196:197], v[62:63], off offset:2048
	global_load_dwordx2 v[204:205], v[62:63], off
	s_nop 0
	global_load_dwordx2 v[16:17], v[16:17], off
	s_nop 0
	global_load_dwordx2 v[206:207], v[38:39], off
	global_load_dwordx2 v[44:45], v[24:25], off
	s_nop 0
	global_load_dwordx2 v[38:39], v[30:31], off
	s_nop 0
	global_load_dwordx2 v[30:31], v[60:61], off
	global_load_dwordx2 v[24:25], v[102:103], off
	s_nop 0
	global_load_dwordx2 v[102:103], v[22:23], off
	global_load_dwordx2 v[60:61], v[26:27], off
	s_nop 0
	global_load_dwordx2 v[54:55], v[54:55], off
	s_nop 0
	global_load_dwordx2 v[18:19], v[18:19], off offset:3584
	v_mov_b32_e32 v9, v3
	v_mov_b32_e32 v7, v1
	v_mov_b32_e32 v22, v2
	v_mov_b32_e32 v23, v2
	v_mov_b32_e32 v26, v0
	v_mov_b32_e32 v27, v0
	s_cmp_lt_u32 s13, 3
	s_waitcnt vmcnt(10)
	v_pk_fma_f32 v[204:205], v[8:9], v[10:11], v[204:205] op_sel:[0,1,0] op_sel_hi:[1,0,1]
	s_nop 0
	v_pk_fma_f32 v[10:11], v[2:3], v[10:11], v[204:205] op_sel_hi:[0,1,1]
	s_waitcnt vmcnt(8)
	v_pk_fma_f32 v[204:205], v[6:7], v[12:13], v[206:207] op_sel:[0,1,0] op_sel_hi:[1,0,1]
	v_pk_fma_f32 v[202:203], v[8:9], v[10:11], v[202:203] op_sel:[0,1,0] op_sel_hi:[1,0,1]
	v_pk_fma_f32 v[12:13], v[0:1], v[12:13], v[204:205] op_sel_hi:[0,1,1]
	v_pk_fma_f32 v[200:201], v[6:7], v[12:13], v[200:201] op_sel:[0,1,0] op_sel_hi:[1,0,1]
	v_pk_fma_f32 v[10:11], v[2:3], v[10:11], v[202:203] op_sel_hi:[0,1,1]
	v_pk_fma_f32 v[12:13], v[0:1], v[12:13], v[200:201] op_sel_hi:[0,1,1]
	s_cbranch_scc1 .LBB0_331
	v_mov_b32_e32 v149, v107
	v_lshl_add_u64 v[200:201], v[4:5], 0, v[148:149]
	global_load_dwordx2 v[62:63], v[62:63], off offset:1024
	s_nop 0
	global_load_dwordx2 v[200:201], v[200:201], off
	s_waitcnt vmcnt(1)
	v_pk_fma_f32 v[62:63], v[8:9], v[10:11], v[62:63] op_sel:[0,1,0] op_sel_hi:[1,0,1]
	s_waitcnt vmcnt(0)
	v_pk_fma_f32 v[200:201], v[6:7], v[12:13], v[200:201] op_sel:[0,1,0] op_sel_hi:[1,0,1]
	v_pk_fma_f32 v[10:11], v[22:23], v[10:11], v[62:63]
	v_pk_fma_f32 v[12:13], v[26:27], v[12:13], v[200:201]

; #define LAS __attribute__((address_space(3)))
; template <bool FINAL>
; __device__ __forceinline__ void ssm_item(const Args& a, LAS unsigned char* lds, int item, int wave, int lane) {
;     ...
;         const f32x2 ec0 = Eb[c0 * 64 + j], ec1 = Eb[c0 * 64 + 32 + j];
;         s0r = (f32x2){c0r, fmaf(t0.x, c0r, fmaf(-t0.y, c0i, ec0.x))}; s0i = (f32x2){c0i, fmaf(t0.x, c0i, fmaf(t0.y, c0r, ec0.y))};
;         s1r = (f32x2){c1r, fmaf(t1.x, c1r, fmaf(-t1.y, c1i, ec1.x))}; s1i = (f32x2){c1i, fmaf(t1.x, c1i, fmaf(t1.y, c1r, ec1.y))};
;     }
;     const int bsel = (j >> 2) & 1, csel = j & 1, tt = ((j & 3) >> 1) + 2 * (j >> 3);
;     const size_t urow0 = meta ? (size_t)META_ROW + tt : (size_t)(b0 + bsel) * SEQ + (size_t)(c0 + csel) * CHUNK + tt;
;     const bf16* up = U + urow0 * DM + g * 16 + 8 * hi;
;     LAS unsigned char* sl = lds + wave * (32 * SP);
;     const int nsteps = meta ? 2 : CHUNK / 8;
;     const size_t erow = (size_t)b0 * SEQ + (size_t)(c0 + ((lane & 15) >> 3)) * CHUNK + (lane & 7);
;     const bf16* ue = U + erow * DM + g * 16 + 4 * (lane >> 4);
;     bf16* ze = Z + erow * DM + g * 16 + 4 * (lane >> 4);
;     bf16x8 uf = *(const bf16x8*)up;
;     u32x2 uu0 = (u32x2){0u, 0u}, uu1 = (u32x2){0u, 0u};
;     if (FINAL) { uu0 = *(const u32x2*)ue; uu1 = *(const u32x2*)(ue + (size_t)SEQ * DM); }
.LBB0_338:
	s_lshl_b32 s21, s20, 7
	s_lshl_b32 s22, s20, 6
	s_and_b32 s21, s21, 0x4000
	s_and_b32 s24, s22, 0x1e00
	s_lshl_b32 s22, s40, 4
	v_or_b32_e32 v6, s21, v161
	s_and_b32 s22, s22, 0x380
	v_or_b32_e32 v6, s24, v6
	s_add_i32 s22, s14, s22
	v_lshlrev_b32_e32 v106, 11, v6
	s_lshl_b32 s22, s22, 1
	s_mov_b32 s23, s11
	s_or_b32 s21, s24, s21
	v_lshl_add_u64 v[6:7], v[106:107], 0, s[22:23]
	v_add_lshl_u32 v106, s21, v241, 11
	s_lshl_b32 s21, s13, 6
	v_or_b32_e32 v14, s21, v130
	v_lshl_add_u64 v[8:9], v[106:107], 0, s[22:23]
	v_lshlrev_b32_e32 v106, 3, v14
	v_or_b32_e32 v16, s21, v104
	v_lshl_add_u64 v[14:15], v[4:5], 0, v[106:107]
	v_lshlrev_b32_e32 v106, 3, v16
	v_lshl_add_u64 v[4:5], v[4:5], 0, v[106:107]
	global_load_dwordx2 v[206:207], v[14:15], off
	global_load_dwordx2 v[204:205], v[4:5], off
	v_or_b32_e32 v4, s12, v163
	v_or_b32_e32 v5, s13, v165
	v_lshlrev_b32_e32 v4, 13, v4
	v_lshlrev_b32_e32 v5, 8, v5
	v_or_b32_e32 v14, s13, v169
	v_or3_b32 v4, v4, v5, v167
	s_lshl_b32 s12, s12, 13
	v_lshlrev_b32_e32 v14, 8, v14
	v_lshlrev_b32_e32 v106, 11, v4
	v_or3_b32 v16, v14, s12, v131
	v_lshl_add_u64 v[4:5], s[52:53], 0, v[106:107]
	v_lshlrev_b32_e32 v106, 11, v16
	s_lshl_b32 s10, s10, 1
	v_lshl_add_u64 v[14:15], s[52:53], 0, v[106:107]
	v_lshl_add_u64 v[4:5], v[4:5], 0, s[10:11]
	v_mov_b32_e32 v189, v107
	v_lshl_add_u64 v[14:15], v[14:15], 0, s[10:11]
	v_mov_b32_e32 v191, v107
	v_lshl_add_u64 v[4:5], v[4:5], 0, v[188:189]
	v_lshl_add_u64 v[14:15], v[14:15], 0, v[190:191]
	global_load_dwordx4 v[100:103], v[4:5], off
	global_load_dwordx2 v[218:219], v[14:15], off
	v_add_co_u32_e32 v4, vcc, 0x1000000, v14
	v_xor_b32_e32 v202, 0x80000000, v195
	s_nop 0
	v_addc_co_u32_e32 v5, vcc, 0, v15, vcc
	global_load_dwordx2 v[212:213], v[4:5], off
	v_xor_b32_e32 v196, 0x80000000, v193
	v_mov_b32_e32 v200, v195
	v_mov_b32_e32 v201, v195
	v_mov_b32_e32 v198, v193
	v_mov_b32_e32 v199, v193
	v_mov_b32_e32 v195, v194
	v_mov_b32_e32 v193, v192
	s_waitcnt vmcnt(6)
	v_mov_b32_e32 v216, v10
	s_waitcnt vmcnt(5)
	v_mov_b32_e32 v214, v12
	v_mov_b32_e32 v203, v202
	v_mov_b32_e32 v197, v196
	v_lshl_add_u64 v[208:209], v[114:115], 0, v[6:7]
	v_lshl_add_u64 v[210:211], v[116:117], 0, v[8:9]
	v_lshlrev_b32_e32 v106, 10, v16
	s_mov_b64 s[12:13], 0
	s_waitcnt vmcnt(4)
	v_fma_f32 v217, -v3, v11, v206
	v_fmac_f32_e32 v207, v3, v10
	s_waitcnt vmcnt(3)
	v_fma_f32 v215, -v1, v13, v204
	v_fmac_f32_e32 v205, v1, v12
	v_fmac_f32_e32 v217, v2, v10
	v_fmac_f32_e32 v207, v2, v11
	v_fmac_f32_e32 v215, v0, v12
	v_fmac_f32_e32 v205, v0, v13
	v_mov_b32_e32 v206, v11
	v_mov_b32_e32 v204, v13
	v_subrev_u32_e32 v137, s58, v208
	v_bfe_u32 v145, v224, 4, 2
	v_lshlrev_b32_e32 v147, 3, v145
	v_sub_u32_e32 v137, v137, v147
	v_lshrrev_b32_e32 v147, 1, v145
	v_lshl_add_u32 v137, v147, 4, v137
	v_and_b32_e32 v147, 1, v145
	v_lshl_add_u32 v137, v147, 24, v137
	v_subrev_u32_e32 v139, s58, v210
	s_add_u32 s76, s58, 0xd104000
	s_addc_u32 s77, s59, 0
	s_add_u32 s78, s58, 0xe104000
	s_addc_u32 s79, s59, 0
	s_add_u32 s66, s58, 0xd108000
	s_addc_u32 s67, s59, 0
	s_add_u32 s68, s58, 0xe108000
	s_addc_u32 s69, s59, 0
	s_add_u32 s70, s58, 0x6e00000
	s_addc_u32 s71, s59, 0
	s_add_u32 s74, s58, 0x7e00000
	s_addc_u32 s75, s59, 0
	s_lshl_b32 s80, s33, 10
	s_add_i32 s80, s80, 0x11000
	v_and_b32_e32 v147, 63, v224
	v_and_b32_e32 v141, 31, v147
	v_lshlrev_b32_e32 v141, 5, v141
	v_lshrrev_b32_e32 v145, 5, v147
	v_lshl_or_b32 v141, v145, 4, v141
	v_add_u32_e32 v141, s80, v141
	v_and_b32_e32 v143, 6, v147
	v_lshlrev_b32_e32 v143, 2, v143
	v_and_b32_e32 v145, 1, v147
	v_lshl_or_b32 v143, v145, 1, v143
	v_bfe_u32 v145, v147, 3, 1
	v_or_b32_e32 v143, v143, v145
	v_lshlrev_b32_e32 v143, 5, v143
	v_lshrrev_b32_e32 v145, 5, v147
	v_lshl_or_b32 v143, v145, 4, v143
	v_bfe_u32 v145, v147, 4, 1
	v_lshl_or_b32 v143, v145, 3, v143
	v_add_u32_e32 v143, s80, v143
	s_mov_b32 s62, 0xbdd2d3e8
	s_mov_b32 s63, 0xbdd2d3e8
	s_mov_b32 s64, 0x3f800000
	s_mov_b32 s65, 0x3f800000
	v_mov_b32_e32 v246, 0xc0135761
	v_add_u32_e32 v245, 0x440, v242
	v_add_u32_e32 v247, 0x880, v242
	v_add_u32_e32 v106, 0xcc0, v242
	v_add_u32_e32 v139, 0x4000, v139
	s_mov_b32 s12, 0
	v_mov_b32_e32 v100, v252
	v_mov_b32_e32 v101, v253
	v_mov_b32_e32 v102, v254
	v_mov_b32_e32 v103, v255
